# combo19 + main W_o units' epilogue: the eight per-row LDS factor reads issued together (was read -> wait -> scale -> store, eight times)
# baseline (speedup 1.0000x reference)
;     __device__ __forceinline__ void operator()(const f32x4 (&acc)[2][2][4][2], const Unit& u, int wr, int wc, int fr, int fq) const {
;     ...
; #pragma unroll
;         for (int ai = 0; ai < 2; ++ai)
; #pragma unroll
;             for (int m = 0; m < 4; ++m) { const int row = row0 + ai * HALF + m * 16; bf16_t* rowp = O + (size_t)row * DM + col0;
;                 float sc = 1.0f; if (SEG) { if (ftab) sc = ftab[(ai * HALF + wr * 64 + m * 16 + fr) * 4 + 2];
;                     else { const float s2 = ss[(size_t)row * 4 + 2]; sc = 1.0f / sqrtf(s2 * (1.0f / 384.0f) + LN_EPS); } }
.LBB0_493:
	s_andn2_b64 vcc, exec, s[0:1]
	v_readlane_b32 s12, v253, 25
	v_readlane_b32 s13, v253, 26
	v_readlane_b32 s14, v253, 27
	v_readlane_b32 s15, v253, 28
	v_readlane_b32 s16, v253, 29
	v_readlane_b32 s17, v253, 30
	v_readlane_b32 s18, v253, 31
	v_readlane_b32 s19, v253, 32
	v_readlane_b32 s20, v253, 33
	v_readlane_b32 s21, v253, 34
	v_readlane_b32 s22, v253, 35
	v_readlane_b32 s23, v253, 36
	v_readlane_b32 s24, v253, 37
	v_readlane_b32 s25, v253, 38
	v_readlane_b32 s26, v253, 39
	v_readlane_b32 s27, v253, 40
	s_cbranch_vccnz .LBB0_527
	v_lshlrev_b32_e32 v0, 4, v17
	s_mov_b64 s[0:1], -1
	s_and_b64 vcc, exec, s[6:7]
	v_add_u32_e32 v17, s30, v0
	s_cbranch_vccz .LBB0_496
	ds_read_b32 v138, v17 offset:8
	ds_read_b32 v243, v17 offset:264
	ds_read_b32 v244, v17 offset:520
	ds_read_b32 v245, v17 offset:776
	ds_read_b32 v246, v17 offset:2056
	ds_read_b32 v247, v17 offset:2312
	ds_read_b32 v248, v17 offset:2568
	ds_read_b32 v249, v17 offset:2824
	s_mov_b64 s[0:1], 0

; __device__ __forceinline__ unsigned cvt_pk_bf16(float lo, float hi) { unsigned r; asm volatile("v_cvt_pk_bf16_f32 %0, %1, %2" : "=v"(r) : "v"(lo), "v"(hi)); return r; }
;     __device__ __forceinline__ void operator()(const f32x4 (&acc)[2][2][4][2], const Unit& u, int wr, int wc, int fr, int fq) const {
;     ...
; #pragma unroll
;                 for (int bj = 0; bj < 2; ++bj) { const f32x4 v0 = acc[ai][bj][m][0] * sc, v1 = acc[ai][bj][m][1] * sc;
;                     u32x4 wv; wv.x = cvt_pk_bf16(v0[0], v0[1]); wv.y = cvt_pk_bf16(v0[2], v0[3]); wv.z = cvt_pk_bf16(v1[0], v1[1]); wv.w = cvt_pk_bf16(v1[2], v1[3]);
;                     *(u32x4*)(rowp + bj * HALF) = wv; } }
.LBB0_498:
	s_add_u32 s6, s10, 0xc300000
	s_addc_u32 s7, s11, 0
	v_lshlrev_b64 v[140:141], 11, v[144:145]
	v_lshl_add_u64 v[140:141], s[6:7], 0, v[140:141]
	v_lshlrev_b32_e32 v0, 1, v150
	v_lshl_add_u64 v[140:141], v[140:141], 0, v[0:1]
	s_waitcnt lgkmcnt(0)
	v_pk_mul_f32 v[132:133], v[132:133], v[138:139] op_sel_hi:[1,0]
	v_pk_mul_f32 v[130:131], v[130:131], v[138:139] op_sel_hi:[1,0]
	v_pk_mul_f32 v[142:143], v[128:129], v[138:139] op_sel_hi:[1,0]
	v_pk_mul_f32 v[128:129], v[126:127], v[138:139] op_sel_hi:[1,0]
	v_cvt_pk_bf16_f32 v126, v130, v131
	v_cvt_pk_bf16_f32 v127, v132, v133
	v_pk_mul_f32 v[122:123], v[122:123], v[138:139] op_sel_hi:[1,0]
	v_cvt_pk_bf16_f32 v128, v128, v129
	v_cvt_pk_bf16_f32 v129, v142, v143
	flat_store_dwordx4 v[140:141], v[126:129]
	s_and_b64 vcc, exec, s[4:5]
	s_mov_b64 s[0:1], -1
	v_pk_mul_f32 v[126:127], v[120:121], v[138:139] op_sel_hi:[1,0]
	v_pk_mul_f32 v[120:121], v[118:119], v[138:139] op_sel_hi:[1,0]
	v_cvt_pk_bf16_f32 v118, v122, v123
	v_pk_mul_f32 v[124:125], v[124:125], v[138:139] op_sel_hi:[1,0]
	s_nop 0
	v_cvt_pk_bf16_f32 v119, v124, v125
	v_cvt_pk_bf16_f32 v120, v120, v121
	v_cvt_pk_bf16_f32 v121, v126, v127
	flat_store_dwordx4 v[140:141], v[118:121] offset:256
	s_cbranch_vccnz .LBB0_500
	s_nop 1
	v_mov_b32_e32 v118, v243
	s_mov_b64 s[0:1], 0

; __device__ __forceinline__ unsigned cvt_pk_bf16(float lo, float hi) { unsigned r; asm volatile("v_cvt_pk_bf16_f32 %0, %1, %2" : "=v"(r) : "v"(lo), "v"(hi)); return r; }
;     __device__ __forceinline__ void operator()(const f32x4 (&acc)[2][2][4][2], const Unit& u, int wr, int wc, int fr, int fq) const {
;     ...
; #pragma unroll
;                 for (int bj = 0; bj < 2; ++bj) { const f32x4 v0 = acc[ai][bj][m][0] * sc, v1 = acc[ai][bj][m][1] * sc;
;                     u32x4 wv; wv.x = cvt_pk_bf16(v0[0], v0[1]); wv.y = cvt_pk_bf16(v0[2], v0[3]); wv.z = cvt_pk_bf16(v1[0], v1[1]); wv.w = cvt_pk_bf16(v1[2], v1[3]);
;                     *(u32x4*)(rowp + bj * HALF) = wv; } }
.LBB0_502:
	v_lshlrev_b64 v[120:121], 11, v[136:137]
	v_lshl_add_u64 v[120:121], s[6:7], 0, v[120:121]
	v_lshl_add_u64 v[120:121], v[120:121], 0, v[0:1]
	s_waitcnt lgkmcnt(0)
	v_pk_mul_f32 v[116:117], v[116:117], v[118:119] op_sel_hi:[1,0]
	v_pk_mul_f32 v[114:115], v[114:115], v[118:119] op_sel_hi:[1,0]
	v_pk_mul_f32 v[122:123], v[112:113], v[118:119] op_sel_hi:[1,0]
	v_pk_mul_f32 v[112:113], v[110:111], v[118:119] op_sel_hi:[1,0]
	v_cvt_pk_bf16_f32 v110, v114, v115
	v_cvt_pk_bf16_f32 v111, v116, v117
	v_pk_mul_f32 v[106:107], v[106:107], v[118:119] op_sel_hi:[1,0]
	v_cvt_pk_bf16_f32 v112, v112, v113
	v_cvt_pk_bf16_f32 v113, v122, v123
	flat_store_dwordx4 v[120:121], v[110:113]
	s_and_b64 vcc, exec, s[4:5]
	s_mov_b64 s[0:1], -1
	v_pk_mul_f32 v[110:111], v[104:105], v[118:119] op_sel_hi:[1,0]
	v_pk_mul_f32 v[104:105], v[102:103], v[118:119] op_sel_hi:[1,0]
	v_cvt_pk_bf16_f32 v102, v106, v107
	v_pk_mul_f32 v[108:109], v[108:109], v[118:119] op_sel_hi:[1,0]
	s_nop 0
	v_cvt_pk_bf16_f32 v103, v108, v109
	v_cvt_pk_bf16_f32 v104, v104, v105
	v_cvt_pk_bf16_f32 v105, v110, v111
	flat_store_dwordx4 v[120:121], v[102:105] offset:256
	s_cbranch_vccnz .LBB0_504
	s_nop 1
	v_mov_b32_e32 v102, v244
	s_mov_b64 s[0:1], 0

; __device__ __forceinline__ unsigned cvt_pk_bf16(float lo, float hi) { unsigned r; asm volatile("v_cvt_pk_bf16_f32 %0, %1, %2" : "=v"(r) : "v"(lo), "v"(hi)); return r; }
;     __device__ __forceinline__ void operator()(const f32x4 (&acc)[2][2][4][2], const Unit& u, int wr, int wc, int fr, int fq) const {
;     ...
; #pragma unroll
;                 for (int bj = 0; bj < 2; ++bj) { const f32x4 v0 = acc[ai][bj][m][0] * sc, v1 = acc[ai][bj][m][1] * sc;
;                     u32x4 wv; wv.x = cvt_pk_bf16(v0[0], v0[1]); wv.y = cvt_pk_bf16(v0[2], v0[3]); wv.z = cvt_pk_bf16(v1[0], v1[1]); wv.w = cvt_pk_bf16(v1[2], v1[3]);
;                     *(u32x4*)(rowp + bj * HALF) = wv; } }
.LBB0_506:
	v_lshlrev_b64 v[104:105], 11, v[134:135]
	v_lshl_add_u64 v[104:105], s[6:7], 0, v[104:105]
	v_lshl_add_u64 v[104:105], v[104:105], 0, v[0:1]
	s_waitcnt lgkmcnt(0)
	v_pk_mul_f32 v[100:101], v[100:101], v[102:103] op_sel_hi:[1,0]
	v_pk_mul_f32 v[98:99], v[98:99], v[102:103] op_sel_hi:[1,0]
	v_pk_mul_f32 v[106:107], v[96:97], v[102:103] op_sel_hi:[1,0]
	v_pk_mul_f32 v[96:97], v[94:95], v[102:103] op_sel_hi:[1,0]
	v_cvt_pk_bf16_f32 v94, v98, v99
	v_cvt_pk_bf16_f32 v95, v100, v101
	v_pk_mul_f32 v[90:91], v[90:91], v[102:103] op_sel_hi:[1,0]
	v_cvt_pk_bf16_f32 v96, v96, v97
	v_cvt_pk_bf16_f32 v97, v106, v107
	flat_store_dwordx4 v[104:105], v[94:97]
	s_and_b64 vcc, exec, s[4:5]
	s_mov_b64 s[0:1], -1
	v_pk_mul_f32 v[94:95], v[88:89], v[102:103] op_sel_hi:[1,0]
	v_pk_mul_f32 v[88:89], v[86:87], v[102:103] op_sel_hi:[1,0]
	v_cvt_pk_bf16_f32 v86, v90, v91
	v_pk_mul_f32 v[92:93], v[92:93], v[102:103] op_sel_hi:[1,0]
	s_nop 0
	v_cvt_pk_bf16_f32 v87, v92, v93
	v_cvt_pk_bf16_f32 v88, v88, v89
	v_cvt_pk_bf16_f32 v89, v94, v95
	flat_store_dwordx4 v[104:105], v[86:89] offset:256
	s_cbranch_vccnz .LBB0_508
	s_nop 1
	v_mov_b32_e32 v86, v245
	s_mov_b64 s[0:1], 0

; __device__ __forceinline__ unsigned cvt_pk_bf16(float lo, float hi) { unsigned r; asm volatile("v_cvt_pk_bf16_f32 %0, %1, %2" : "=v"(r) : "v"(lo), "v"(hi)); return r; }
;     __device__ __forceinline__ void operator()(const f32x4 (&acc)[2][2][4][2], const Unit& u, int wr, int wc, int fr, int fq) const {
;     ...
; #pragma unroll
;                 for (int bj = 0; bj < 2; ++bj) { const f32x4 v0 = acc[ai][bj][m][0] * sc, v1 = acc[ai][bj][m][1] * sc;
;                     u32x4 wv; wv.x = cvt_pk_bf16(v0[0], v0[1]); wv.y = cvt_pk_bf16(v0[2], v0[3]); wv.z = cvt_pk_bf16(v1[0], v1[1]); wv.w = cvt_pk_bf16(v1[2], v1[3]);
;                     *(u32x4*)(rowp + bj * HALF) = wv; } }
.LBB0_510:
	v_lshlrev_b64 v[2:3], 11, v[2:3]
	v_lshl_add_u64 v[2:3], s[6:7], 0, v[2:3]
	v_lshl_add_u64 v[2:3], v[2:3], 0, v[0:1]
	s_waitcnt lgkmcnt(0)
	v_pk_mul_f32 v[84:85], v[84:85], v[86:87] op_sel_hi:[1,0]
	v_pk_mul_f32 v[82:83], v[82:83], v[86:87] op_sel_hi:[1,0]
	v_pk_mul_f32 v[88:89], v[80:81], v[86:87] op_sel_hi:[1,0]
	v_pk_mul_f32 v[80:81], v[78:79], v[86:87] op_sel_hi:[1,0]
	v_cvt_pk_bf16_f32 v78, v82, v83
	v_cvt_pk_bf16_f32 v79, v84, v85
	v_pk_mul_f32 v[74:75], v[74:75], v[86:87] op_sel_hi:[1,0]
	v_cvt_pk_bf16_f32 v80, v80, v81
	v_cvt_pk_bf16_f32 v81, v88, v89
	flat_store_dwordx4 v[2:3], v[78:81]
	s_and_b64 vcc, exec, s[4:5]
	s_mov_b64 s[0:1], -1
	v_pk_mul_f32 v[78:79], v[72:73], v[86:87] op_sel_hi:[1,0]
	v_pk_mul_f32 v[72:73], v[70:71], v[86:87] op_sel_hi:[1,0]
	v_cvt_pk_bf16_f32 v70, v74, v75
	v_pk_mul_f32 v[76:77], v[76:77], v[86:87] op_sel_hi:[1,0]
	s_nop 0
	v_cvt_pk_bf16_f32 v71, v76, v77
	v_cvt_pk_bf16_f32 v72, v72, v73
	v_cvt_pk_bf16_f32 v73, v78, v79
	flat_store_dwordx4 v[2:3], v[70:73] offset:256
	s_cbranch_vccnz .LBB0_512
	s_nop 1
	v_mov_b32_e32 v70, v246
	s_mov_b64 s[0:1], 0

; __device__ __forceinline__ unsigned cvt_pk_bf16(float lo, float hi) { unsigned r; asm volatile("v_cvt_pk_bf16_f32 %0, %1, %2" : "=v"(r) : "v"(lo), "v"(hi)); return r; }
;     __device__ __forceinline__ void operator()(const f32x4 (&acc)[2][2][4][2], const Unit& u, int wr, int wc, int fr, int fq) const {
;     ...
; #pragma unroll
;                 for (int bj = 0; bj < 2; ++bj) { const f32x4 v0 = acc[ai][bj][m][0] * sc, v1 = acc[ai][bj][m][1] * sc;
;                     u32x4 wv; wv.x = cvt_pk_bf16(v0[0], v0[1]); wv.y = cvt_pk_bf16(v0[2], v0[3]); wv.z = cvt_pk_bf16(v1[0], v1[1]); wv.w = cvt_pk_bf16(v1[2], v1[3]);
;                     *(u32x4*)(rowp + bj * HALF) = wv; } }
.LBB0_514:
	v_lshlrev_b64 v[2:3], 11, v[2:3]
	v_lshl_add_u64 v[2:3], s[6:7], 0, v[2:3]
	v_lshl_add_u64 v[2:3], v[2:3], 0, v[0:1]
	s_waitcnt lgkmcnt(0)
	v_pk_mul_f32 v[68:69], v[68:69], v[70:71] op_sel_hi:[1,0]
	v_pk_mul_f32 v[66:67], v[66:67], v[70:71] op_sel_hi:[1,0]
	v_pk_mul_f32 v[72:73], v[64:65], v[70:71] op_sel_hi:[1,0]
	v_pk_mul_f32 v[64:65], v[62:63], v[70:71] op_sel_hi:[1,0]
	v_cvt_pk_bf16_f32 v62, v66, v67
	v_cvt_pk_bf16_f32 v63, v68, v69
	v_pk_mul_f32 v[58:59], v[58:59], v[70:71] op_sel_hi:[1,0]
	v_cvt_pk_bf16_f32 v64, v64, v65
	v_cvt_pk_bf16_f32 v65, v72, v73
	flat_store_dwordx4 v[2:3], v[62:65]
	s_and_b64 vcc, exec, s[4:5]
	s_mov_b64 s[0:1], -1
	v_pk_mul_f32 v[62:63], v[56:57], v[70:71] op_sel_hi:[1,0]
	v_pk_mul_f32 v[56:57], v[54:55], v[70:71] op_sel_hi:[1,0]
	v_cvt_pk_bf16_f32 v54, v58, v59
	v_pk_mul_f32 v[60:61], v[60:61], v[70:71] op_sel_hi:[1,0]
	s_nop 0
	v_cvt_pk_bf16_f32 v55, v60, v61
	v_cvt_pk_bf16_f32 v56, v56, v57
	v_cvt_pk_bf16_f32 v57, v62, v63
	flat_store_dwordx4 v[2:3], v[54:57] offset:256
	s_cbranch_vccnz .LBB0_516
	s_nop 1
	v_mov_b32_e32 v54, v247
	s_mov_b64 s[0:1], 0

; __device__ __forceinline__ unsigned cvt_pk_bf16(float lo, float hi) { unsigned r; asm volatile("v_cvt_pk_bf16_f32 %0, %1, %2" : "=v"(r) : "v"(lo), "v"(hi)); return r; }
;     __device__ __forceinline__ void operator()(const f32x4 (&acc)[2][2][4][2], const Unit& u, int wr, int wc, int fr, int fq) const {
;     ...
; #pragma unroll
;                 for (int bj = 0; bj < 2; ++bj) { const f32x4 v0 = acc[ai][bj][m][0] * sc, v1 = acc[ai][bj][m][1] * sc;
;                     u32x4 wv; wv.x = cvt_pk_bf16(v0[0], v0[1]); wv.y = cvt_pk_bf16(v0[2], v0[3]); wv.z = cvt_pk_bf16(v1[0], v1[1]); wv.w = cvt_pk_bf16(v1[2], v1[3]);
;                     *(u32x4*)(rowp + bj * HALF) = wv; } }
.LBB0_518:
	v_lshlrev_b64 v[2:3], 11, v[2:3]
	v_lshl_add_u64 v[2:3], s[6:7], 0, v[2:3]
	v_lshl_add_u64 v[2:3], v[2:3], 0, v[0:1]
	s_waitcnt lgkmcnt(0)
	v_pk_mul_f32 v[52:53], v[52:53], v[54:55] op_sel_hi:[1,0]
	v_pk_mul_f32 v[50:51], v[50:51], v[54:55] op_sel_hi:[1,0]
	v_pk_mul_f32 v[56:57], v[48:49], v[54:55] op_sel_hi:[1,0]
	v_pk_mul_f32 v[48:49], v[46:47], v[54:55] op_sel_hi:[1,0]
	v_cvt_pk_bf16_f32 v46, v50, v51
	v_cvt_pk_bf16_f32 v47, v52, v53
	v_pk_mul_f32 v[42:43], v[42:43], v[54:55] op_sel_hi:[1,0]
	v_cvt_pk_bf16_f32 v48, v48, v49
	v_cvt_pk_bf16_f32 v49, v56, v57
	flat_store_dwordx4 v[2:3], v[46:49]
	s_and_b64 vcc, exec, s[4:5]
	s_mov_b64 s[0:1], -1
	v_pk_mul_f32 v[46:47], v[40:41], v[54:55] op_sel_hi:[1,0]
	v_pk_mul_f32 v[40:41], v[38:39], v[54:55] op_sel_hi:[1,0]
	v_cvt_pk_bf16_f32 v38, v42, v43
	v_pk_mul_f32 v[44:45], v[44:45], v[54:55] op_sel_hi:[1,0]
	s_nop 0
	v_cvt_pk_bf16_f32 v39, v44, v45
	v_cvt_pk_bf16_f32 v40, v40, v41
	v_cvt_pk_bf16_f32 v41, v46, v47
	flat_store_dwordx4 v[2:3], v[38:41] offset:256
	s_cbranch_vccnz .LBB0_520
	s_nop 1
	v_mov_b32_e32 v38, v248
	s_mov_b64 s[0:1], 0

; __device__ __forceinline__ unsigned cvt_pk_bf16(float lo, float hi) { unsigned r; asm volatile("v_cvt_pk_bf16_f32 %0, %1, %2" : "=v"(r) : "v"(lo), "v"(hi)); return r; }
;     __device__ __forceinline__ void operator()(const f32x4 (&acc)[2][2][4][2], const Unit& u, int wr, int wc, int fr, int fq) const {
;     ...
; #pragma unroll
;                 for (int bj = 0; bj < 2; ++bj) { const f32x4 v0 = acc[ai][bj][m][0] * sc, v1 = acc[ai][bj][m][1] * sc;
;                     u32x4 wv; wv.x = cvt_pk_bf16(v0[0], v0[1]); wv.y = cvt_pk_bf16(v0[2], v0[3]); wv.z = cvt_pk_bf16(v1[0], v1[1]); wv.w = cvt_pk_bf16(v1[2], v1[3]);
;                     *(u32x4*)(rowp + bj * HALF) = wv; } }
.LBB0_522:
	v_lshlrev_b64 v[2:3], 11, v[2:3]
	v_lshl_add_u64 v[2:3], s[6:7], 0, v[2:3]
	v_lshl_add_u64 v[2:3], v[2:3], 0, v[0:1]
	s_waitcnt lgkmcnt(0)
	v_pk_mul_f32 v[36:37], v[36:37], v[38:39] op_sel_hi:[1,0]
	v_pk_mul_f32 v[34:35], v[34:35], v[38:39] op_sel_hi:[1,0]
	v_pk_mul_f32 v[40:41], v[32:33], v[38:39] op_sel_hi:[1,0]
	v_pk_mul_f32 v[32:33], v[30:31], v[38:39] op_sel_hi:[1,0]
	v_cvt_pk_bf16_f32 v30, v34, v35
	v_cvt_pk_bf16_f32 v31, v36, v37
	v_pk_mul_f32 v[26:27], v[26:27], v[38:39] op_sel_hi:[1,0]
	v_cvt_pk_bf16_f32 v32, v32, v33
	v_cvt_pk_bf16_f32 v33, v40, v41
	flat_store_dwordx4 v[2:3], v[30:33]
	s_and_b64 vcc, exec, s[4:5]
	s_mov_b64 s[0:1], -1
	v_pk_mul_f32 v[30:31], v[24:25], v[38:39] op_sel_hi:[1,0]
	v_pk_mul_f32 v[24:25], v[22:23], v[38:39] op_sel_hi:[1,0]
	v_cvt_pk_bf16_f32 v22, v26, v27
	v_pk_mul_f32 v[28:29], v[28:29], v[38:39] op_sel_hi:[1,0]
	s_nop 0
	v_cvt_pk_bf16_f32 v23, v28, v29
	v_cvt_pk_bf16_f32 v24, v24, v25
	v_cvt_pk_bf16_f32 v25, v30, v31
	flat_store_dwordx4 v[2:3], v[22:25] offset:256
	s_cbranch_vccnz .LBB0_524
	s_nop 1
	v_mov_b32_e32 v22, v249
	s_mov_b64 s[0:1], 0
